# out-projection epilogue (first-layer f32 residual variant): x loads pipelined, stores no longer drained per chunk
# speedup vs baseline: 1.0048x; 1.0048x over previous
; #define PG8_STAGE(bufoff, gbase, voff) do { _Pragma("unroll") for (int _i = 0; _i < 2; ++_i) \
;         __builtin_amdgcn_global_load_lds((const unsigned*)((const char*)(gbase) + (voff)[_i]), (LAS unsigned*)(lds + (bufoff) + ldsw + _i * 8192), 16, 0, 0); } while (0)
; #define PG8_LDA(dst, b, h) do { _Pragma("unroll") for (int m = 0; m < 4; ++m) _Pragma("unroll") for (int k = 0; k < 2; ++k) dst[m][k] = *(const LAS h8*)(lds + PG8_SA(b, h) + aoff + m * 2048 + k * 1024); } while (0)
; #define PG8_LDB(dst, b, h) do { _Pragma("unroll") for (int n = 0; n < 2; ++n) _Pragma("unroll") for (int k = 0; k < 2; ++k) dst[n][k] = *(const LAS h8*)(lds + PG8_SB(b, h) + boff + n * 2048 + k * 1024); } while (0)
; #define PG8_WAIT_V(n) asm volatile("s_waitcnt vmcnt(" #n ")" ::: "memory")
; #define PG8_WAIT_L(n) asm volatile("s_waitcnt lgkmcnt(" #n ")" ::: "memory")
; #define PG8_BAR __builtin_amdgcn_s_barrier()
; #define PG8_SCHED __builtin_amdgcn_sched_barrier(0)
; template <class Epi>
; __device__ __forceinline__ void gemm_phase(LAS unsigned char* lds, const Gemm g, const StaticOrder& S, const Epi& E, const int tid) {
;     ...
;         for (int t = 0; t < nt; t += 2) {
;             const bool last = (t == nt - 2);
;             const char* a1 = cA + (size_t)(t + 1) * kstep;
;             const char* a2 = last ? nA : cA + (size_t)(t + 2) * kstep; const char* b2 = last ? nB : cB + (size_t)(t + 2) * kstep;
;             const char* a3 = a2 + kstep; const char* b3 = b2 + kstep;
;             if constexpr (Epi::HAS_MID) { if (t == (nt >> 1)) E.mid(acc, cur, wr, wc, fr, fq); }
;             PG8_LDB(B0, 0, 0); PG8_SCHED; PG8_LDA(At, 0, 0); PG8_STAGE(PG8_SA(1, 1), a1 + hstep, voffA);
;             PG8_WAIT_L(8); PG8_BAR; PG8_WAIT_L(0); PG8_MMA(0, 0, At, B0); PG8_BAR; PG8_SCHED;
;             PG8_LDB(B1, 0, 1); PG8_STAGE(PG8_SB(0, 0), b2, voffB);
;             PG8_BAR; PG8_WAIT_L(0); PG8_MMA(0, 1, At, B1); PG8_BAR;
;             PG8_LDA(At, 0, 1); PG8_STAGE(PG8_SA(0, 0), a2, voffA);
;             PG8_BAR; PG8_WAIT_L(0); PG8_MMA(1, 0, At, B0); PG8_BAR; PG8_SCHED;
;             PG8_STAGE(PG8_SB(0, 1), b2 + hstepB, voffB);
;             PG8_WAIT_V(6); PG8_BAR; PG8_MMA(1, 1, At, B1); PG8_BAR;
.LBB0_678:
	s_add_u32 s14, s12, 0xfff80080
	s_addc_u32 s15, s13, -1
	s_add_i32 s55, 0, 0x10000
	v_add_u32_e32 v88, s55, v176
	ds_read_b128 v[68:71], v88
	ds_read_b128 v[72:75], v88 offset:1024
	ds_read_b128 v[84:87], v88 offset:2048
	ds_read_b128 v[88:91], v88 offset:3072
	s_cmp_eq_u32 s54, 28
	s_cselect_b32 s19, s7, s15
	s_cselect_b32 s18, s50, s14
	s_cselect_b32 s15, s1, s53
	s_cselect_b32 s14, s51, s52
	v_lshl_add_u64 v[174:175], s[12:13], 0, v[166:167]
	s_add_i32 m0, s39, 0xc000
	ds_read_b128 v[170:173], v177
	ds_read_b128 v[190:193], v177 offset:1024
	ds_read_b128 v[194:197], v177 offset:2048
	ds_read_b128 v[198:201], v177 offset:3072
	ds_read_b128 v[202:205], v177 offset:4096
	ds_read_b128 v[206:209], v177 offset:5120
	ds_read_b128 v[210:213], v177 offset:6144
	ds_read_b128 v[214:217], v177 offset:7168
	global_load_lds_dwordx4 v[174:175], off
	v_lshl_add_u64 v[174:175], s[12:13], 0, v[168:169]
	s_add_i32 m0, s39, 0xe000
	s_nop 0
	global_load_lds_dwordx4 v[174:175], off
	s_waitcnt lgkmcnt(8)
	s_barrier
	s_waitcnt lgkmcnt(0)
	s_setprio 1
	s_waitcnt lgkmcnt(0)
	v_mfma_f32_16x16x32_bf16 v[144:147], v[68:71], v[170:173], v[144:147]
	v_mfma_f32_16x16x32_bf16 v[140:143], v[84:87], v[170:173], v[140:143]
	v_mfma_f32_16x16x32_bf16 v[128:131], v[68:71], v[194:197], v[128:131]
	v_mfma_f32_16x16x32_bf16 v[124:127], v[84:87], v[194:197], v[124:127]
	v_mfma_f32_16x16x32_bf16 v[112:115], v[68:71], v[202:205], v[112:115]
	v_mfma_f32_16x16x32_bf16 v[108:111], v[84:87], v[202:205], v[108:111]
	v_mfma_f32_16x16x32_bf16 v[96:99], v[68:71], v[210:213], v[96:99]
	v_mfma_f32_16x16x32_bf16 v[92:95], v[84:87], v[210:213], v[92:95]
	v_mfma_f32_16x16x32_bf16 v[144:147], v[72:75], v[190:193], v[144:147]
	v_mfma_f32_16x16x32_bf16 v[140:143], v[88:91], v[190:193], v[140:143]
	v_mfma_f32_16x16x32_bf16 v[128:131], v[72:75], v[198:201], v[128:131]
	v_mfma_f32_16x16x32_bf16 v[124:127], v[88:91], v[198:201], v[124:127]
	v_mfma_f32_16x16x32_bf16 v[112:115], v[72:75], v[206:209], v[112:115]
	v_mfma_f32_16x16x32_bf16 v[108:111], v[88:91], v[206:209], v[108:111]
	v_mfma_f32_16x16x32_bf16 v[96:99], v[72:75], v[214:217], v[96:99]
	v_mfma_f32_16x16x32_bf16 v[92:95], v[88:91], v[214:217], v[92:95]
	s_setprio 0
	s_barrier
	s_add_i32 s58, 0, 0x14000
	v_add_u32_e32 v174, s58, v176
	s_add_i32 s55, s55, s38
	ds_read_b128 v[218:221], v174
	ds_read_b128 v[222:225], v174 offset:1024
	ds_read_b128 v[226:229], v174 offset:2048
	ds_read_b128 v[230:233], v174 offset:3072
	v_lshl_add_u64 v[174:175], s[14:15], 0, v[2:3]
	s_mov_b32 m0, s55
	v_lshl_add_u64 v[234:235], s[14:15], 0, v[0:1]
	global_load_lds_dwordx4 v[174:175], off
	s_add_i32 m0, s55, 0x2000
	s_nop 0
	global_load_lds_dwordx4 v[234:235], off
	s_barrier
	s_waitcnt lgkmcnt(0)
	s_setprio 1
	s_waitcnt lgkmcnt(0)
	v_mfma_f32_16x16x32_bf16 v[136:139], v[218:221], v[170:173], v[136:139]
	v_mfma_f32_16x16x32_bf16 v[132:135], v[226:229], v[170:173], v[132:135]
	v_mfma_f32_16x16x32_bf16 v[120:123], v[218:221], v[194:197], v[120:123]
	v_mfma_f32_16x16x32_bf16 v[116:119], v[226:229], v[194:197], v[116:119]
	v_mfma_f32_16x16x32_bf16 v[104:107], v[218:221], v[202:205], v[104:107]
	v_mfma_f32_16x16x32_bf16 v[100:103], v[226:229], v[202:205], v[100:103]
	v_mfma_f32_16x16x32_bf16 v[80:83], v[218:221], v[210:213], v[80:83]
	v_mfma_f32_16x16x32_bf16 v[76:79], v[226:229], v[210:213], v[76:79]
	v_mfma_f32_16x16x32_bf16 v[136:139], v[222:225], v[190:193], v[136:139]
	v_mfma_f32_16x16x32_bf16 v[132:135], v[230:233], v[190:193], v[132:135]
	v_mfma_f32_16x16x32_bf16 v[120:123], v[222:225], v[198:201], v[120:123]
	v_mfma_f32_16x16x32_bf16 v[116:119], v[230:233], v[198:201], v[116:119]
	v_mfma_f32_16x16x32_bf16 v[104:107], v[222:225], v[206:209], v[104:107]
	v_mfma_f32_16x16x32_bf16 v[100:103], v[230:233], v[206:209], v[100:103]
	v_mfma_f32_16x16x32_bf16 v[80:83], v[222:225], v[214:217], v[80:83]
	v_mfma_f32_16x16x32_bf16 v[76:79], v[230:233], v[214:217], v[76:79]
	s_setprio 0
	s_mov_b32 m0, s39
	v_lshl_add_u64 v[236:237], s[18:19], 0, v[164:165]
	s_barrier
	ds_read_b128 v[170:173], v177 offset:16384
	ds_read_b128 v[190:193], v177 offset:17408
	ds_read_b128 v[194:197], v177 offset:18432
	ds_read_b128 v[198:201], v177 offset:19456
	ds_read_b128 v[202:205], v177 offset:20480
	ds_read_b128 v[206:209], v177 offset:21504
	ds_read_b128 v[210:213], v177 offset:22528
	ds_read_b128 v[214:217], v177 offset:23552
	global_load_lds_dwordx4 v[236:237], off
	v_lshl_add_u64 v[238:239], s[18:19], 0, v[162:163]
	s_mov_b32 m0, s40
	s_nop 0
	global_load_lds_dwordx4 v[238:239], off
	s_barrier
	s_waitcnt lgkmcnt(0)
	s_setprio 1
	s_waitcnt lgkmcnt(0)
	v_mfma_f32_16x16x32_bf16 v[64:67], v[68:71], v[170:173], v[64:67]
	v_mfma_f32_16x16x32_bf16 v[60:63], v[84:87], v[170:173], v[60:63]
	v_mfma_f32_16x16x32_bf16 v[48:51], v[68:71], v[194:197], v[48:51]
	v_mfma_f32_16x16x32_bf16 v[44:47], v[84:87], v[194:197], v[44:47]
	v_mfma_f32_16x16x32_bf16 v[32:35], v[68:71], v[202:205], v[32:35]
	v_mfma_f32_16x16x32_bf16 v[28:31], v[84:87], v[202:205], v[28:31]
	v_mfma_f32_16x16x32_bf16 v[16:19], v[68:71], v[210:213], v[16:19]
	v_mfma_f32_16x16x32_bf16 v[12:15], v[84:87], v[210:213], v[12:15]
	v_mfma_f32_16x16x32_bf16 v[64:67], v[72:75], v[190:193], v[64:67]
	v_mfma_f32_16x16x32_bf16 v[60:63], v[88:91], v[190:193], v[60:63]
	v_mfma_f32_16x16x32_bf16 v[48:51], v[72:75], v[198:201], v[48:51]
	v_mfma_f32_16x16x32_bf16 v[44:47], v[88:91], v[198:201], v[44:47]
	v_mfma_f32_16x16x32_bf16 v[32:35], v[72:75], v[206:209], v[32:35]
	v_mfma_f32_16x16x32_bf16 v[28:31], v[88:91], v[206:209], v[28:31]
	v_mfma_f32_16x16x32_bf16 v[16:19], v[72:75], v[214:217], v[16:19]
	v_mfma_f32_16x16x32_bf16 v[12:15], v[88:91], v[214:217], v[12:15]
	s_setprio 0
	s_barrier
; #define PG8_STAGE(bufoff, gbase, voff) do { _Pragma("unroll") for (int _i = 0; _i < 2; ++_i) \
;         __builtin_amdgcn_global_load_lds((const unsigned*)((const char*)(gbase) + (voff)[_i]), (LAS unsigned*)(lds + (bufoff) + ldsw + _i * 8192), 16, 0, 0); } while (0)
; #define PG8_LDA(dst, b, h) do { _Pragma("unroll") for (int m = 0; m < 4; ++m) _Pragma("unroll") for (int k = 0; k < 2; ++k) dst[m][k] = *(const LAS h8*)(lds + PG8_SA(b, h) + aoff + m * 2048 + k * 1024); } while (0)
; #define PG8_LDB(dst, b, h) do { _Pragma("unroll") for (int n = 0; n < 2; ++n) _Pragma("unroll") for (int k = 0; k < 2; ++k) dst[n][k] = *(const LAS h8*)(lds + PG8_SB(b, h) + boff + n * 2048 + k * 1024); } while (0)
; #define PG8_WAIT_V(n) asm volatile("s_waitcnt vmcnt(" #n ")" ::: "memory")
; #define PG8_WAIT_L(n) asm volatile("s_waitcnt lgkmcnt(" #n ")" ::: "memory")
; #define PG8_BAR __builtin_amdgcn_s_barrier()
; #define PG8_SCHED __builtin_amdgcn_sched_barrier(0)
; template <class Epi>
; __device__ __forceinline__ void gemm_phase(LAS unsigned char* lds, const Gemm g, const StaticOrder& S, const Epi& E, const int tid) {
;     ...
;             PG8_STAGE(PG8_SB(0, 1), b2 + hstepB, voffB);
;             PG8_WAIT_V(6); PG8_BAR; PG8_MMA(1, 1, At, B1); PG8_BAR;
;             PG8_LDB(B0, 1, 0); PG8_SCHED; PG8_LDA(At, 1, 0); PG8_STAGE(PG8_SA(0, 1), a2 + hstep, voffA);
;             PG8_WAIT_L(8); PG8_BAR; PG8_WAIT_L(0); PG8_MMA(0, 0, At, B0); PG8_BAR; PG8_SCHED;
;             PG8_LDB(B1, 1, 1); PG8_STAGE(PG8_SB(1, 0), b3, voffB);
;             PG8_BAR; PG8_WAIT_L(0); PG8_MMA(0, 1, At, B1); PG8_BAR;
;             PG8_LDA(At, 1, 1); PG8_STAGE(PG8_SA(1, 0), a3, voffA);
;             PG8_BAR; PG8_WAIT_L(0); PG8_MMA(1, 0, At, B0); PG8_BAR; PG8_SCHED;
	s_add_u32 s56, s14, 0x80000
	s_addc_u32 s57, s15, 0
	s_add_i32 s55, s58, s38
	v_lshl_add_u64 v[68:69], s[56:57], 0, v[2:3]
	s_mov_b32 m0, s55
	s_nop 0
	global_load_lds_dwordx4 v[68:69], off
	v_lshl_add_u64 v[68:69], s[56:57], 0, v[0:1]
	s_add_i32 m0, s55, 0x2000
	s_nop 0
	global_load_lds_dwordx4 v[68:69], off
	s_waitcnt vmcnt(6)
	s_barrier
	s_setprio 1
	v_mfma_f32_16x16x32_bf16 v[56:59], v[218:221], v[170:173], v[56:59]
	v_mfma_f32_16x16x32_bf16 v[52:55], v[226:229], v[170:173], v[52:55]
	v_mfma_f32_16x16x32_bf16 v[40:43], v[218:221], v[194:197], v[40:43]
	v_mfma_f32_16x16x32_bf16 v[36:39], v[226:229], v[194:197], v[36:39]
	v_mfma_f32_16x16x32_bf16 v[24:27], v[218:221], v[202:205], v[24:27]
	v_mfma_f32_16x16x32_bf16 v[20:23], v[226:229], v[202:205], v[20:23]
	v_mfma_f32_16x16x32_bf16 v[8:11], v[218:221], v[210:213], v[8:11]
	v_mfma_f32_16x16x32_bf16 v[4:7], v[226:229], v[210:213], v[4:7]
	v_mfma_f32_16x16x32_bf16 v[56:59], v[222:225], v[190:193], v[56:59]
	v_mfma_f32_16x16x32_bf16 v[52:55], v[230:233], v[190:193], v[52:55]
	v_mfma_f32_16x16x32_bf16 v[40:43], v[222:225], v[198:201], v[40:43]
	v_mfma_f32_16x16x32_bf16 v[36:39], v[230:233], v[198:201], v[36:39]
	v_mfma_f32_16x16x32_bf16 v[24:27], v[222:225], v[206:209], v[24:27]
	v_mfma_f32_16x16x32_bf16 v[20:23], v[230:233], v[206:209], v[20:23]
	v_mfma_f32_16x16x32_bf16 v[8:11], v[222:225], v[214:217], v[8:11]
	v_mfma_f32_16x16x32_bf16 v[4:7], v[230:233], v[214:217], v[4:7]
	s_setprio 0
	s_add_i32 s55, 0, 0x18000
	v_add_u32_e32 v88, s55, v176
	s_barrier
	ds_read_b128 v[68:71], v88
	ds_read_b128 v[72:75], v88 offset:1024
	ds_read_b128 v[84:87], v88 offset:2048
	ds_read_b128 v[88:91], v88 offset:3072
	s_add_u32 s18, s18, 0x80000
	s_addc_u32 s19, s19, 0
	s_mov_b32 m0, s41
	v_lshl_add_u64 v[218:219], s[18:19], 0, v[164:165]
	ds_read_b128 v[170:173], v177 offset:32768
	ds_read_b128 v[190:193], v177 offset:33792
	ds_read_b128 v[194:197], v177 offset:34816
	ds_read_b128 v[198:201], v177 offset:35840
	ds_read_b128 v[202:205], v177 offset:36864
	ds_read_b128 v[206:209], v177 offset:37888
	ds_read_b128 v[210:213], v177 offset:38912
	ds_read_b128 v[214:217], v177 offset:39936
	global_load_lds_dwordx4 v[218:219], off
	v_lshl_add_u64 v[218:219], s[18:19], 0, v[162:163]
	s_mov_b32 m0, s42
	s_nop 0
	global_load_lds_dwordx4 v[218:219], off
	s_waitcnt lgkmcnt(8)
	s_barrier
	s_waitcnt lgkmcnt(0)
	s_setprio 1
	s_waitcnt lgkmcnt(0)
	v_mfma_f32_16x16x32_bf16 v[144:147], v[68:71], v[170:173], v[144:147]
	v_mfma_f32_16x16x32_bf16 v[140:143], v[84:87], v[170:173], v[140:143]
	v_mfma_f32_16x16x32_bf16 v[128:131], v[68:71], v[194:197], v[128:131]
	v_mfma_f32_16x16x32_bf16 v[124:127], v[84:87], v[194:197], v[124:127]
	v_mfma_f32_16x16x32_bf16 v[112:115], v[68:71], v[202:205], v[112:115]
	v_mfma_f32_16x16x32_bf16 v[108:111], v[84:87], v[202:205], v[108:111]
	v_mfma_f32_16x16x32_bf16 v[96:99], v[68:71], v[210:213], v[96:99]
	v_mfma_f32_16x16x32_bf16 v[92:95], v[84:87], v[210:213], v[92:95]
	v_mfma_f32_16x16x32_bf16 v[144:147], v[72:75], v[190:193], v[144:147]
	v_mfma_f32_16x16x32_bf16 v[140:143], v[88:91], v[190:193], v[140:143]
	v_mfma_f32_16x16x32_bf16 v[128:131], v[72:75], v[198:201], v[128:131]
	v_mfma_f32_16x16x32_bf16 v[124:127], v[88:91], v[198:201], v[124:127]
	v_mfma_f32_16x16x32_bf16 v[112:115], v[72:75], v[206:209], v[112:115]
	v_mfma_f32_16x16x32_bf16 v[108:111], v[88:91], v[206:209], v[108:111]
	v_mfma_f32_16x16x32_bf16 v[96:99], v[72:75], v[214:217], v[96:99]
	v_mfma_f32_16x16x32_bf16 v[92:95], v[88:91], v[214:217], v[92:95]
	s_setprio 0
	s_barrier
	s_add_i32 s18, 0, 0x1c000
	s_add_i32 s19, s55, s38
	v_add_u32_e32 v178, s18, v176
	v_lshl_add_u64 v[174:175], v[174:175], 0, s[30:31]
	s_mov_b32 m0, s19
	ds_read_b128 v[218:221], v178
	ds_read_b128 v[222:225], v178 offset:1024
	ds_read_b128 v[226:229], v178 offset:2048
	ds_read_b128 v[230:233], v178 offset:3072
	global_load_lds_dwordx4 v[174:175], off
	v_lshl_add_u64 v[174:175], v[234:235], 0, s[30:31]
	s_add_i32 m0, s19, 0x2000
	s_nop 0
	global_load_lds_dwordx4 v[174:175], off
	s_barrier
	s_waitcnt lgkmcnt(0)
	s_setprio 1
	s_waitcnt lgkmcnt(0)
	v_mfma_f32_16x16x32_bf16 v[136:139], v[218:221], v[170:173], v[136:139]
	v_mfma_f32_16x16x32_bf16 v[132:135], v[226:229], v[170:173], v[132:135]
	v_mfma_f32_16x16x32_bf16 v[120:123], v[218:221], v[194:197], v[120:123]
	v_mfma_f32_16x16x32_bf16 v[116:119], v[226:229], v[194:197], v[116:119]
	v_mfma_f32_16x16x32_bf16 v[104:107], v[218:221], v[202:205], v[104:107]
	v_mfma_f32_16x16x32_bf16 v[100:103], v[226:229], v[202:205], v[100:103]
	v_mfma_f32_16x16x32_bf16 v[80:83], v[218:221], v[210:213], v[80:83]
	v_mfma_f32_16x16x32_bf16 v[76:79], v[226:229], v[210:213], v[76:79]
	v_mfma_f32_16x16x32_bf16 v[136:139], v[222:225], v[190:193], v[136:139]
	v_mfma_f32_16x16x32_bf16 v[132:135], v[230:233], v[190:193], v[132:135]
	v_mfma_f32_16x16x32_bf16 v[120:123], v[222:225], v[198:201], v[120:123]
	v_mfma_f32_16x16x32_bf16 v[116:119], v[230:233], v[198:201], v[116:119]
	v_mfma_f32_16x16x32_bf16 v[104:107], v[222:225], v[206:209], v[104:107]
	v_mfma_f32_16x16x32_bf16 v[100:103], v[230:233], v[206:209], v[100:103]
	v_mfma_f32_16x16x32_bf16 v[80:83], v[222:225], v[214:217], v[80:83]
	v_mfma_f32_16x16x32_bf16 v[76:79], v[230:233], v[214:217], v[76:79]
	s_setprio 0
	s_mov_b32 m0, s43
	v_lshl_add_u64 v[174:175], v[236:237], 0, s[30:31]
	s_barrier
	ds_read_b128 v[170:173], v177 offset:49152
	ds_read_b128 v[190:193], v177 offset:50176
	ds_read_b128 v[194:197], v177 offset:51200
	ds_read_b128 v[198:201], v177 offset:52224
	ds_read_b128 v[202:205], v177 offset:53248
	ds_read_b128 v[206:209], v177 offset:54272
	ds_read_b128 v[210:213], v177 offset:55296
	ds_read_b128 v[214:217], v177 offset:56320
	global_load_lds_dwordx4 v[174:175], off
	v_lshl_add_u64 v[174:175], v[238:239], 0, s[30:31]
	s_mov_b32 m0, s46
	s_nop 0
	global_load_lds_dwordx4 v[174:175], off
	s_barrier
; #define PG8_STAGE(bufoff, gbase, voff) do { _Pragma("unroll") for (int _i = 0; _i < 2; ++_i) \
;         __builtin_amdgcn_global_load_lds((const unsigned*)((const char*)(gbase) + (voff)[_i]), (LAS unsigned*)(lds + (bufoff) + ldsw + _i * 8192), 16, 0, 0); } while (0)
; #define PG8_WAIT_V(n) asm volatile("s_waitcnt vmcnt(" #n ")" ::: "memory")
; template <class Epi>
; __device__ __forceinline__ void gemm_phase(LAS unsigned char* lds, const Gemm g, const StaticOrder& S, const Epi& E, const int tid) {
;     ...
;             PG8_BAR; PG8_WAIT_L(0); PG8_MMA(0, 1, At, B1); PG8_BAR;
;             PG8_LDA(At, 1, 1); PG8_STAGE(PG8_SA(1, 0), a3, voffA);
;             PG8_BAR; PG8_WAIT_L(0); PG8_MMA(1, 0, At, B0); PG8_BAR; PG8_SCHED;
;             PG8_STAGE(PG8_SB(1, 1), b3 + hstepB, voffB);
;             PG8_WAIT_V(6); PG8_BAR; PG8_MMA(1, 1, At, B1); PG8_BAR;
;     __device__ __forceinline__ void operator()(const f32x4 (&acc)[2][2][4][2], const pg8::Unit& u, int wr, int wc, int fr, int fq) const {
;         const int row0 = u.pm * 256 + wr * 64 + fr, col0 = u.pn * 256 + wc * 32 + 8 * fq;
;         const float* gp = gate + (size_t)((u.pm * 256) >> 12) * 6144 + col0;
;         f32x4 gv[2][2];
; #pragma unroll
;         for (int bj = 0; bj < 2; ++bj)
; #pragma unroll
;             for (int n = 0; n < 2; ++n) gv[bj][n] = *(const f32x4*)(gp + bj * 128 + 4 * n);
; #pragma unroll
;         for (int ai = 0; ai < 2; ++ai)
; #pragma unroll
;             for (int m = 0; m < 4; ++m) { const size_t ro = (size_t)(row0 + ai * 128 + m * 16) * DM + col0;
; #pragma unroll
;                 for (int bj = 0; bj < 2; ++bj) {
;                     f32x4 x0, x1;
;                     if (XF32) { x0 = *(const f32x4*)(xin + ro + bj * 128); x1 = *(const f32x4*)(xin + ro + bj * 128 + 4); }
;                     else { const h8 xh = *(const h8*)(H + ro + bj * 128); x0 = (f32x4){(float)xh[0], (float)xh[1], (float)xh[2], (float)xh[3]}; x1 = (f32x4){(float)xh[4], (float)xh[5], (float)xh[6], (float)xh[7]}; }
;                     const f32x4 y0 = x0 + gv[bj][0] * acc[ai][bj][m][0], y1 = x1 + gv[bj][1] * acc[ai][bj][m][1];
;                     h8 o; o[0] = (half_t)y0[0]; o[1] = (half_t)y0[1]; o[2] = (half_t)y0[2]; o[3] = (half_t)y0[3]; o[4] = (half_t)y1[0]; o[5] = (half_t)y1[1]; o[6] = (half_t)y1[2]; o[7] = (half_t)y1[3];
;                     *(h8*)(H + ro + bj * 128) = o; } }
	s_waitcnt lgkmcnt(0)
	s_setprio 1
	s_waitcnt lgkmcnt(0)
	v_mfma_f32_16x16x32_bf16 v[64:67], v[68:71], v[170:173], v[64:67]
	v_mfma_f32_16x16x32_bf16 v[60:63], v[84:87], v[170:173], v[60:63]
	v_mfma_f32_16x16x32_bf16 v[48:51], v[68:71], v[194:197], v[48:51]
	v_mfma_f32_16x16x32_bf16 v[44:47], v[84:87], v[194:197], v[44:47]
	v_mfma_f32_16x16x32_bf16 v[32:35], v[68:71], v[202:205], v[32:35]
	v_mfma_f32_16x16x32_bf16 v[28:31], v[84:87], v[202:205], v[28:31]
	v_mfma_f32_16x16x32_bf16 v[16:19], v[68:71], v[210:213], v[16:19]
	v_mfma_f32_16x16x32_bf16 v[12:15], v[84:87], v[210:213], v[12:15]
	v_mfma_f32_16x16x32_bf16 v[64:67], v[72:75], v[190:193], v[64:67]
	v_mfma_f32_16x16x32_bf16 v[60:63], v[88:91], v[190:193], v[60:63]
	v_mfma_f32_16x16x32_bf16 v[48:51], v[72:75], v[198:201], v[48:51]
	v_mfma_f32_16x16x32_bf16 v[44:47], v[88:91], v[198:201], v[44:47]
	v_mfma_f32_16x16x32_bf16 v[32:35], v[72:75], v[206:209], v[32:35]
	v_mfma_f32_16x16x32_bf16 v[28:31], v[88:91], v[206:209], v[28:31]
	v_mfma_f32_16x16x32_bf16 v[16:19], v[72:75], v[214:217], v[16:19]
	v_mfma_f32_16x16x32_bf16 v[12:15], v[88:91], v[214:217], v[12:15]
	s_setprio 0
	s_barrier
	s_add_u32 s14, s14, 0x80080
	s_addc_u32 s15, s15, 0
	s_add_i32 s18, s18, s38
	v_lshl_add_u64 v[68:69], s[14:15], 0, v[2:3]
	s_mov_b32 m0, s18
	s_nop 0
	global_load_lds_dwordx4 v[68:69], off
	v_lshl_add_u64 v[68:69], s[14:15], 0, v[0:1]
	s_add_i32 m0, s18, 0x2000
	s_nop 0
	global_load_lds_dwordx4 v[68:69], off
	s_waitcnt vmcnt(6)
	s_barrier
	s_setprio 1
	v_mfma_f32_16x16x32_bf16 v[56:59], v[218:221], v[170:173], v[56:59]
	v_mfma_f32_16x16x32_bf16 v[52:55], v[226:229], v[170:173], v[52:55]
	v_mfma_f32_16x16x32_bf16 v[40:43], v[218:221], v[194:197], v[40:43]
	v_mfma_f32_16x16x32_bf16 v[36:39], v[226:229], v[194:197], v[36:39]
	v_mfma_f32_16x16x32_bf16 v[24:27], v[218:221], v[202:205], v[24:27]
	v_mfma_f32_16x16x32_bf16 v[20:23], v[226:229], v[202:205], v[20:23]
	v_mfma_f32_16x16x32_bf16 v[8:11], v[218:221], v[210:213], v[8:11]
	v_mfma_f32_16x16x32_bf16 v[4:7], v[226:229], v[210:213], v[4:7]
	v_mfma_f32_16x16x32_bf16 v[56:59], v[222:225], v[190:193], v[56:59]
	v_mfma_f32_16x16x32_bf16 v[52:55], v[230:233], v[190:193], v[52:55]
	v_mfma_f32_16x16x32_bf16 v[40:43], v[222:225], v[198:201], v[40:43]
	v_mfma_f32_16x16x32_bf16 v[36:39], v[230:233], v[198:201], v[36:39]
	v_mfma_f32_16x16x32_bf16 v[24:27], v[222:225], v[206:209], v[24:27]
	v_mfma_f32_16x16x32_bf16 v[20:23], v[230:233], v[206:209], v[20:23]
	v_mfma_f32_16x16x32_bf16 v[8:11], v[222:225], v[214:217], v[8:11]
	v_mfma_f32_16x16x32_bf16 v[4:7], v[230:233], v[214:217], v[4:7]
	s_setprio 0
	s_add_i32 s54, s54, 2
	s_add_u32 s12, s12, 0x100
	s_addc_u32 s13, s13, 0
	s_add_u32 s52, s52, 0x100
	s_addc_u32 s53, s53, 0
	s_cmp_gt_u32 s54, 29
	s_barrier
	s_cbranch_scc0 .LBB0_678
	s_ashr_i32 s1, s48, 4
	v_lshl_add_u32 v174, s48, 8, v179
	v_lshl_or_b32 v172, s49, 8, v157
	s_mul_hi_i32 s7, s1, 0x6000
	s_mulk_i32 s1, 0x6000
	v_ashrrev_i32_e32 v175, 31, v174
	s_add_u32 s12, s23, s1
	v_ashrrev_i32_e32 v173, 31, v172
	v_lshlrev_b64 v[170:171], 11, v[174:175]
	s_addc_u32 s13, s24, s7
	v_lshl_add_u64 v[170:171], v[170:171], 0, v[172:173]
	v_lshl_add_u64 v[72:73], v[172:173], 2, s[12:13]
	v_lshl_add_u64 v[198:199], v[170:171], 2, s[80:81]
	global_load_dwordx4 v[84:87], v[72:73], off offset:16
	global_load_dwordx4 v[88:91], v[72:73], off
	global_load_dwordx4 v[68:71], v[72:73], off offset:528
	s_nop 0
	global_load_dwordx4 v[72:75], v[72:73], off offset:512
	s_mov_b64 s[98:99], 0x0
	v_lshl_add_u64 v[248:249], v[198:199], 0, s[98:99]
	global_load_dwordx4 v[200:203], v[248:249], off offset:16
	global_load_dwordx4 v[204:207], v[248:249], off
	s_mov_b64 s[98:99], 0x0
	v_lshl_add_u64 v[248:249], v[198:199], 0, s[98:99]
	global_load_dwordx4 v[208:211], v[248:249], off offset:528
	global_load_dwordx4 v[212:215], v[248:249], off offset:512
	s_mov_b64 s[98:99], 0x20000
	v_lshl_add_u64 v[248:249], v[198:199], 0, s[98:99]
	global_load_dwordx4 v[216:219], v[248:249], off offset:16
	global_load_dwordx4 v[220:223], v[248:249], off
	s_mov_b64 s[98:99], 0x20000
	v_lshl_add_u64 v[248:249], v[198:199], 0, s[98:99]
	global_load_dwordx4 v[224:227], v[248:249], off offset:528
	global_load_dwordx4 v[228:231], v[248:249], off offset:512
	s_mov_b64 s[98:99], 0x40000
	v_lshl_add_u64 v[248:249], v[198:199], 0, s[98:99]
	global_load_dwordx4 v[232:235], v[248:249], off offset:16
	global_load_dwordx4 v[236:239], v[248:249], off
	s_mov_b64 s[98:99], 0x40000
	v_lshl_add_u64 v[248:249], v[198:199], 0, s[98:99]
	global_load_dwordx4 v[240:243], v[248:249], off offset:528
	global_load_dwordx4 v[244:247], v[248:249], off offset:512
	s_nop 0
	s_nop 1
	s_waitcnt vmcnt(10)
	v_mov_b32_e32 v190, v200
	v_mov_b32_e32 v191, v201
	v_mov_b32_e32 v192, v202
	v_mov_b32_e32 v193, v203
	s_nop 1
	v_mov_b32_e32 v194, v204
	v_mov_b32_e32 v195, v205
	v_mov_b32_e32 v196, v206
	v_mov_b32_e32 v197, v207
	s_mov_b64 s[98:99], 0x60000
	v_lshl_add_u64 v[248:249], v[198:199], 0, s[98:99]
	global_load_dwordx4 v[200:203], v[248:249], off offset:16
	global_load_dwordx4 v[204:207], v[248:249], off
	s_mov_b64 s[12:13], 0x40000
	s_and_b64 vcc, exec, s[4:5]
	s_mov_b32 s49, s0
	s_mov_b32 s48, s6
	s_mov_b64 s[14:15], s[10:11]
	s_nop 0
	v_pk_fma_f32 v[142:143], v[142:143], v[86:87], v[192:193]
	v_pk_fma_f32 v[146:147], v[146:147], v[90:91], v[196:197]
	v_pk_fma_f32 v[144:145], v[144:145], v[88:89], v[194:195]
	v_pk_fma_f32 v[190:191], v[140:141], v[84:85], v[190:191]
	v_cvt_pk_f16_f32 v143, v142, v143
	v_cvt_pk_f16_f32 v141, v146, v147
	v_cvt_pk_f16_f32 v142, v190, v191
	v_cvt_pk_f16_f32 v140, v144, v145
	v_lshl_add_u64 v[190:191], v[170:171], 1, s[16:17]
	global_store_dwordx4 v[190:191], v[140:143], off
	s_nop 1
	s_waitcnt vmcnt(10)
;     __device__ __forceinline__ void operator()(const f32x4 (&acc)[2][2][4][2], const pg8::Unit& u, int wr, int wc, int fr, int fq) const {
;     ...
;         for (int ai = 0; ai < 2; ++ai)
; #pragma unroll
;             for (int m = 0; m < 4; ++m) { const size_t ro = (size_t)(row0 + ai * 128 + m * 16) * DM + col0;
; #pragma unroll
;                 for (int bj = 0; bj < 2; ++bj) {
;                     f32x4 x0, x1;
;                     if (XF32) { x0 = *(const f32x4*)(xin + ro + bj * 128); x1 = *(const f32x4*)(xin + ro + bj * 128 + 4); }
;                     else { const h8 xh = *(const h8*)(H + ro + bj * 128); x0 = (f32x4){(float)xh[0], (float)xh[1], (float)xh[2], (float)xh[3]}; x1 = (f32x4){(float)xh[4], (float)xh[5], (float)xh[6], (float)xh[7]}; }
;                     const f32x4 y0 = x0 + gv[bj][0] * acc[ai][bj][m][0], y1 = x1 + gv[bj][1] * acc[ai][bj][m][1];
;                     h8 o; o[0] = (half_t)y0[0]; o[1] = (half_t)y0[1]; o[2] = (half_t)y0[2]; o[3] = (half_t)y0[3]; o[4] = (half_t)y1[0]; o[5] = (half_t)y1[1]; o[6] = (half_t)y1[2]; o[7] = (half_t)y1[3];
;                     *(h8*)(H + ro + bj * 128) = o; } }
	v_mov_b32_e32 v140, v208
	v_mov_b32_e32 v141, v209
	v_mov_b32_e32 v142, v210
	v_mov_b32_e32 v143, v211
	s_nop 0
	s_nop 1
	v_mov_b32_e32 v144, v212
	v_mov_b32_e32 v145, v213
	v_mov_b32_e32 v146, v214
	v_mov_b32_e32 v147, v215
	s_mov_b64 s[98:99], 0x60000
	v_lshl_add_u64 v[248:249], v[198:199], 0, s[98:99]
	global_load_dwordx4 v[208:211], v[248:249], off offset:528
	global_load_dwordx4 v[212:215], v[248:249], off offset:512
	s_nop 0
	v_pk_fma_f32 v[134:135], v[134:135], v[70:71], v[142:143]
	v_pk_fma_f32 v[138:139], v[138:139], v[74:75], v[146:147]
	v_pk_fma_f32 v[136:137], v[136:137], v[72:73], v[144:145]
	v_pk_fma_f32 v[140:141], v[132:133], v[68:69], v[140:141]
	v_cvt_pk_f16_f32 v135, v134, v135
	v_cvt_pk_f16_f32 v133, v138, v139
	v_cvt_pk_f16_f32 v134, v140, v141
	v_cvt_pk_f16_f32 v132, v136, v137
	global_store_dwordx4 v[190:191], v[132:135], off offset:256
	s_nop 1
	v_or_b32_e32 v132, 16, v174
	v_ashrrev_i32_e32 v133, 31, v132
	v_lshlrev_b64 v[132:133], 11, v[132:133]
	v_lshl_add_u64 v[140:141], v[132:133], 0, v[172:173]
	v_lshl_add_u64 v[142:143], v[140:141], 2, s[80:81]
	s_nop 1
	s_waitcnt vmcnt(10)
	v_mov_b32_e32 v132, v216
	v_mov_b32_e32 v133, v217
	v_mov_b32_e32 v134, v218
	v_mov_b32_e32 v135, v219
	s_nop 1
	v_mov_b32_e32 v136, v220
	v_mov_b32_e32 v137, v221
	v_mov_b32_e32 v138, v222
	v_mov_b32_e32 v139, v223
	s_mov_b64 s[98:99], 0x100000
	v_lshl_add_u64 v[248:249], v[198:199], 0, s[98:99]
	global_load_dwordx4 v[216:219], v[248:249], off offset:16
	global_load_dwordx4 v[220:223], v[248:249], off
	s_nop 0
	v_pk_fma_f32 v[126:127], v[126:127], v[86:87], v[134:135]
	v_pk_fma_f32 v[130:131], v[130:131], v[90:91], v[138:139]
	v_pk_fma_f32 v[128:129], v[128:129], v[88:89], v[136:137]
	v_pk_fma_f32 v[132:133], v[124:125], v[84:85], v[132:133]
	v_cvt_pk_f16_f32 v127, v126, v127
	v_cvt_pk_f16_f32 v125, v130, v131
	v_cvt_pk_f16_f32 v126, v132, v133
	v_cvt_pk_f16_f32 v124, v128, v129
	v_lshl_add_u64 v[132:133], v[140:141], 1, s[16:17]
	global_store_dwordx4 v[132:133], v[124:127], off
	s_nop 1
	s_waitcnt vmcnt(10)
	v_mov_b32_e32 v124, v224
	v_mov_b32_e32 v125, v225
	v_mov_b32_e32 v126, v226
	v_mov_b32_e32 v127, v227
	s_nop 0
	s_nop 1
	v_mov_b32_e32 v128, v228
	v_mov_b32_e32 v129, v229
	v_mov_b32_e32 v130, v230
	v_mov_b32_e32 v131, v231
	s_mov_b64 s[98:99], 0x100000
	v_lshl_add_u64 v[248:249], v[198:199], 0, s[98:99]
	global_load_dwordx4 v[224:227], v[248:249], off offset:528
	global_load_dwordx4 v[228:231], v[248:249], off offset:512
	s_nop 0
	v_pk_fma_f32 v[118:119], v[118:119], v[70:71], v[126:127]
	v_pk_fma_f32 v[122:123], v[122:123], v[74:75], v[130:131]
	v_pk_fma_f32 v[120:121], v[120:121], v[72:73], v[128:129]
	v_pk_fma_f32 v[124:125], v[116:117], v[68:69], v[124:125]
	v_cvt_pk_f16_f32 v119, v118, v119
	v_cvt_pk_f16_f32 v117, v122, v123
	v_cvt_pk_f16_f32 v118, v124, v125
	v_cvt_pk_f16_f32 v116, v120, v121
	global_store_dwordx4 v[132:133], v[116:119], off offset:256
	s_nop 1
	v_or_b32_e32 v116, 32, v174
	v_ashrrev_i32_e32 v117, 31, v116
	v_lshlrev_b64 v[116:117], 11, v[116:117]
	v_lshl_add_u64 v[124:125], v[116:117], 0, v[172:173]
	v_lshl_add_u64 v[126:127], v[124:125], 2, s[80:81]
	s_nop 1
	s_waitcnt vmcnt(10)
	v_mov_b32_e32 v116, v232
	v_mov_b32_e32 v117, v233
	v_mov_b32_e32 v118, v234
	v_mov_b32_e32 v119, v235
	s_nop 1
	v_mov_b32_e32 v120, v236
	v_mov_b32_e32 v121, v237
	v_mov_b32_e32 v122, v238
	v_mov_b32_e32 v123, v239
	s_mov_b64 s[98:99], 0x120000
	v_lshl_add_u64 v[248:249], v[198:199], 0, s[98:99]
	global_load_dwordx4 v[232:235], v[248:249], off offset:16
	global_load_dwordx4 v[236:239], v[248:249], off
	s_nop 0
	v_pk_fma_f32 v[110:111], v[110:111], v[86:87], v[118:119]
	v_pk_fma_f32 v[114:115], v[114:115], v[90:91], v[122:123]
	v_pk_fma_f32 v[112:113], v[112:113], v[88:89], v[120:121]
	v_pk_fma_f32 v[116:117], v[108:109], v[84:85], v[116:117]
	v_cvt_pk_f16_f32 v111, v110, v111
	v_cvt_pk_f16_f32 v109, v114, v115
	v_cvt_pk_f16_f32 v110, v116, v117
	v_cvt_pk_f16_f32 v108, v112, v113
	v_lshl_add_u64 v[116:117], v[124:125], 1, s[16:17]
	global_store_dwordx4 v[116:117], v[108:111], off
	s_nop 1
	s_waitcnt vmcnt(10)
	v_mov_b32_e32 v108, v240
	v_mov_b32_e32 v109, v241
	v_mov_b32_e32 v110, v242
	v_mov_b32_e32 v111, v243
	s_nop 0
	s_nop 1
	v_mov_b32_e32 v112, v244
	v_mov_b32_e32 v113, v245
	v_mov_b32_e32 v114, v246
	v_mov_b32_e32 v115, v247
	s_mov_b64 s[98:99], 0x120000
	v_lshl_add_u64 v[248:249], v[198:199], 0, s[98:99]
	global_load_dwordx4 v[240:243], v[248:249], off offset:528
	global_load_dwordx4 v[244:247], v[248:249], off offset:512
	s_nop 0
	v_pk_fma_f32 v[102:103], v[102:103], v[70:71], v[110:111]
	v_pk_fma_f32 v[106:107], v[106:107], v[74:75], v[114:115]
	v_pk_fma_f32 v[104:105], v[104:105], v[72:73], v[112:113]
	v_pk_fma_f32 v[108:109], v[100:101], v[68:69], v[108:109]
	v_cvt_pk_f16_f32 v103, v102, v103
	v_cvt_pk_f16_f32 v101, v106, v107
	v_cvt_pk_f16_f32 v102, v108, v109
	v_cvt_pk_f16_f32 v100, v104, v105
	global_store_dwordx4 v[116:117], v[100:103], off offset:256
	s_nop 1
	v_or_b32_e32 v100, 48, v174
	v_ashrrev_i32_e32 v101, 31, v100
	v_lshlrev_b64 v[100:101], 11, v[100:101]
	v_lshl_add_u64 v[108:109], v[100:101], 0, v[172:173]
	v_lshl_add_u64 v[110:111], v[108:109], 2, s[80:81]
	s_nop 1
	s_waitcnt vmcnt(10)
;     __device__ __forceinline__ void operator()(const f32x4 (&acc)[2][2][4][2], const pg8::Unit& u, int wr, int wc, int fr, int fq) const {
;     ...
;         for (int ai = 0; ai < 2; ++ai)
; #pragma unroll
;             for (int m = 0; m < 4; ++m) { const size_t ro = (size_t)(row0 + ai * 128 + m * 16) * DM + col0;
; #pragma unroll
;                 for (int bj = 0; bj < 2; ++bj) {
;                     f32x4 x0, x1;
;                     if (XF32) { x0 = *(const f32x4*)(xin + ro + bj * 128); x1 = *(const f32x4*)(xin + ro + bj * 128 + 4); }
;                     else { const h8 xh = *(const h8*)(H + ro + bj * 128); x0 = (f32x4){(float)xh[0], (float)xh[1], (float)xh[2], (float)xh[3]}; x1 = (f32x4){(float)xh[4], (float)xh[5], (float)xh[6], (float)xh[7]}; }
;                     const f32x4 y0 = x0 + gv[bj][0] * acc[ai][bj][m][0], y1 = x1 + gv[bj][1] * acc[ai][bj][m][1];
;                     h8 o; o[0] = (half_t)y0[0]; o[1] = (half_t)y0[1]; o[2] = (half_t)y0[2]; o[3] = (half_t)y0[3]; o[4] = (half_t)y1[0]; o[5] = (half_t)y1[1]; o[6] = (half_t)y1[2]; o[7] = (half_t)y1[3];
;                     *(h8*)(H + ro + bj * 128) = o; } }
	v_mov_b32_e32 v100, v200
	v_mov_b32_e32 v101, v201
	v_mov_b32_e32 v102, v202
	v_mov_b32_e32 v103, v203
	s_nop 1
	v_mov_b32_e32 v104, v204
	v_mov_b32_e32 v105, v205
	v_mov_b32_e32 v106, v206
	v_mov_b32_e32 v107, v207
	s_mov_b64 s[98:99], 0x140000
	v_lshl_add_u64 v[248:249], v[198:199], 0, s[98:99]
	global_load_dwordx4 v[200:203], v[248:249], off offset:16
	global_load_dwordx4 v[204:207], v[248:249], off
	s_nop 0
	v_pk_fma_f32 v[94:95], v[94:95], v[86:87], v[102:103]
	v_pk_fma_f32 v[98:99], v[98:99], v[90:91], v[106:107]
	v_pk_fma_f32 v[96:97], v[96:97], v[88:89], v[104:105]
	v_pk_fma_f32 v[100:101], v[92:93], v[84:85], v[100:101]
	v_cvt_pk_f16_f32 v95, v94, v95
	v_cvt_pk_f16_f32 v93, v98, v99
	v_cvt_pk_f16_f32 v94, v100, v101
	v_cvt_pk_f16_f32 v92, v96, v97
	v_lshl_add_u64 v[100:101], v[108:109], 1, s[16:17]
	global_store_dwordx4 v[100:101], v[92:95], off
	s_nop 1
	s_waitcnt vmcnt(10)
	v_mov_b32_e32 v92, v208
	v_mov_b32_e32 v93, v209
	v_mov_b32_e32 v94, v210
	v_mov_b32_e32 v95, v211
	s_nop 0
	s_nop 1
	v_mov_b32_e32 v96, v212
	v_mov_b32_e32 v97, v213
	v_mov_b32_e32 v98, v214
	v_mov_b32_e32 v99, v215
	s_mov_b64 s[98:99], 0x140000
	v_lshl_add_u64 v[248:249], v[198:199], 0, s[98:99]
	global_load_dwordx4 v[208:211], v[248:249], off offset:528
	global_load_dwordx4 v[212:215], v[248:249], off offset:512
	s_nop 0
	v_pk_fma_f32 v[78:79], v[78:79], v[70:71], v[94:95]
	v_pk_fma_f32 v[82:83], v[82:83], v[74:75], v[98:99]
	v_pk_fma_f32 v[80:81], v[80:81], v[72:73], v[96:97]
	v_pk_fma_f32 v[92:93], v[76:77], v[68:69], v[92:93]
	v_cvt_pk_f16_f32 v79, v78, v79
	v_cvt_pk_f16_f32 v77, v82, v83
	v_cvt_pk_f16_f32 v78, v92, v93
	v_cvt_pk_f16_f32 v76, v80, v81
	v_lshl_add_u64 v[92:93], v[170:171], 0, s[12:13]
	global_store_dwordx4 v[100:101], v[76:79], off offset:256
	v_lshl_add_u64 v[94:95], v[92:93], 2, s[80:81]
	s_nop 1
	s_waitcnt vmcnt(10)
	v_mov_b32_e32 v76, v216
	v_mov_b32_e32 v77, v217
	v_mov_b32_e32 v78, v218
	v_mov_b32_e32 v79, v219
	s_nop 1
	v_mov_b32_e32 v80, v220
	v_mov_b32_e32 v81, v221
	v_mov_b32_e32 v82, v222
	v_mov_b32_e32 v83, v223
	s_mov_b64 s[98:99], 0x160000
	v_lshl_add_u64 v[248:249], v[198:199], 0, s[98:99]
	global_load_dwordx4 v[216:219], v[248:249], off offset:16
	global_load_dwordx4 v[220:223], v[248:249], off
	s_mov_b64 s[12:13], 0x48000
	s_nop 0
	v_pk_fma_f32 v[62:63], v[62:63], v[86:87], v[78:79]
	v_pk_fma_f32 v[66:67], v[66:67], v[90:91], v[82:83]
	v_pk_fma_f32 v[64:65], v[64:65], v[88:89], v[80:81]
	v_pk_fma_f32 v[76:77], v[60:61], v[84:85], v[76:77]
	v_cvt_pk_f16_f32 v63, v62, v63
	v_cvt_pk_f16_f32 v61, v66, v67
	v_cvt_pk_f16_f32 v62, v76, v77
	v_cvt_pk_f16_f32 v60, v64, v65
	v_lshl_add_u64 v[76:77], v[92:93], 1, s[16:17]
	global_store_dwordx4 v[76:77], v[60:63], off
	s_nop 1
	s_waitcnt vmcnt(10)
	v_mov_b32_e32 v60, v224
	v_mov_b32_e32 v61, v225
	v_mov_b32_e32 v62, v226
	v_mov_b32_e32 v63, v227
	s_nop 0
	s_nop 1
	v_mov_b32_e32 v64, v228
	v_mov_b32_e32 v65, v229
	v_mov_b32_e32 v66, v230
	v_mov_b32_e32 v67, v231
	s_mov_b64 s[98:99], 0x160000
	v_lshl_add_u64 v[248:249], v[198:199], 0, s[98:99]
	global_load_dwordx4 v[224:227], v[248:249], off offset:528
	global_load_dwordx4 v[228:231], v[248:249], off offset:512
	s_nop 0
	v_pk_fma_f32 v[54:55], v[54:55], v[70:71], v[62:63]
	v_pk_fma_f32 v[58:59], v[58:59], v[74:75], v[66:67]
	v_pk_fma_f32 v[56:57], v[56:57], v[72:73], v[64:65]
	v_pk_fma_f32 v[60:61], v[52:53], v[68:69], v[60:61]
	v_cvt_pk_f16_f32 v55, v54, v55
	v_cvt_pk_f16_f32 v53, v58, v59
	v_cvt_pk_f16_f32 v54, v60, v61
	v_cvt_pk_f16_f32 v52, v56, v57
	v_lshl_add_u64 v[60:61], v[170:171], 0, s[12:13]
	global_store_dwordx4 v[76:77], v[52:55], off offset:256
	v_lshl_add_u64 v[62:63], v[60:61], 2, s[80:81]
	s_nop 1
	s_waitcnt vmcnt(10)
	v_mov_b32_e32 v52, v232
	v_mov_b32_e32 v53, v233
	v_mov_b32_e32 v54, v234
	v_mov_b32_e32 v55, v235
	s_nop 1
	v_mov_b32_e32 v56, v236
	v_mov_b32_e32 v57, v237
	v_mov_b32_e32 v58, v238
	v_mov_b32_e32 v59, v239
	s_mov_b64 s[12:13], 0x50000
	s_nop 0
	v_pk_fma_f32 v[46:47], v[46:47], v[86:87], v[54:55]
	v_pk_fma_f32 v[50:51], v[50:51], v[90:91], v[58:59]
	v_pk_fma_f32 v[48:49], v[48:49], v[88:89], v[56:57]
	v_pk_fma_f32 v[52:53], v[44:45], v[84:85], v[52:53]
	v_cvt_pk_f16_f32 v47, v46, v47
	v_cvt_pk_f16_f32 v45, v50, v51
	v_cvt_pk_f16_f32 v46, v52, v53
	v_cvt_pk_f16_f32 v44, v48, v49
	v_lshl_add_u64 v[52:53], v[60:61], 1, s[16:17]
	global_store_dwordx4 v[52:53], v[44:47], off
	s_nop 1
	s_waitcnt vmcnt(8)
; template <class Epi>
; __device__ __forceinline__ void gemm_phase(LAS unsigned char* lds, const Gemm g, const StaticOrder& S, const Epi& E, const int tid) {
;     ...
;         E(acc, cur, wr, wc, fr, fq);
;         if (!has_next) break;
;     __device__ __forceinline__ void operator()(const f32x4 (&acc)[2][2][4][2], const pg8::Unit& u, int wr, int wc, int fr, int fq) const {
;     ...
;         for (int ai = 0; ai < 2; ++ai)
; #pragma unroll
;             for (int m = 0; m < 4; ++m) { const size_t ro = (size_t)(row0 + ai * 128 + m * 16) * DM + col0;
; #pragma unroll
;                 for (int bj = 0; bj < 2; ++bj) {
;                     f32x4 x0, x1;
;                     if (XF32) { x0 = *(const f32x4*)(xin + ro + bj * 128); x1 = *(const f32x4*)(xin + ro + bj * 128 + 4); }
;                     else { const h8 xh = *(const h8*)(H + ro + bj * 128); x0 = (f32x4){(float)xh[0], (float)xh[1], (float)xh[2], (float)xh[3]}; x1 = (f32x4){(float)xh[4], (float)xh[5], (float)xh[6], (float)xh[7]}; }
;                     const f32x4 y0 = x0 + gv[bj][0] * acc[ai][bj][m][0], y1 = x1 + gv[bj][1] * acc[ai][bj][m][1];
;                     h8 o; o[0] = (half_t)y0[0]; o[1] = (half_t)y0[1]; o[2] = (half_t)y0[2]; o[3] = (half_t)y0[3]; o[4] = (half_t)y1[0]; o[5] = (half_t)y1[1]; o[6] = (half_t)y1[2]; o[7] = (half_t)y1[3];
;                     *(h8*)(H + ro + bj * 128) = o; } }
	v_mov_b32_e32 v44, v240
	v_mov_b32_e32 v45, v241
	v_mov_b32_e32 v46, v242
	v_mov_b32_e32 v47, v243
	s_nop 0
	s_nop 1
	v_mov_b32_e32 v48, v244
	v_mov_b32_e32 v49, v245
	v_mov_b32_e32 v50, v246
	v_mov_b32_e32 v51, v247
	s_nop 0
	v_pk_fma_f32 v[38:39], v[38:39], v[70:71], v[46:47]
	v_pk_fma_f32 v[42:43], v[42:43], v[74:75], v[50:51]
	v_pk_fma_f32 v[40:41], v[40:41], v[72:73], v[48:49]
	v_pk_fma_f32 v[44:45], v[36:37], v[68:69], v[44:45]
	v_cvt_pk_f16_f32 v39, v38, v39
	v_cvt_pk_f16_f32 v37, v42, v43
	v_cvt_pk_f16_f32 v38, v44, v45
	v_cvt_pk_f16_f32 v36, v40, v41
	v_lshl_add_u64 v[44:45], v[170:171], 0, s[12:13]
	global_store_dwordx4 v[52:53], v[36:39], off offset:256
	v_lshl_add_u64 v[46:47], v[44:45], 2, s[80:81]
	s_nop 1
	s_waitcnt vmcnt(6)
	v_mov_b32_e32 v36, v200
	v_mov_b32_e32 v37, v201
	v_mov_b32_e32 v38, v202
	v_mov_b32_e32 v39, v203
	s_nop 1
	v_mov_b32_e32 v40, v204
	v_mov_b32_e32 v41, v205
	v_mov_b32_e32 v42, v206
	v_mov_b32_e32 v43, v207
	s_mov_b64 s[12:13], 0x58000
	s_nop 0
	v_pk_fma_f32 v[30:31], v[30:31], v[86:87], v[38:39]
	v_pk_fma_f32 v[34:35], v[34:35], v[90:91], v[42:43]
	v_pk_fma_f32 v[32:33], v[32:33], v[88:89], v[40:41]
	v_pk_fma_f32 v[36:37], v[28:29], v[84:85], v[36:37]
	v_cvt_pk_f16_f32 v31, v30, v31
	v_cvt_pk_f16_f32 v29, v34, v35
	v_cvt_pk_f16_f32 v30, v36, v37
	v_cvt_pk_f16_f32 v28, v32, v33
	v_lshl_add_u64 v[36:37], v[44:45], 1, s[16:17]
	global_store_dwordx4 v[36:37], v[28:31], off
	s_nop 1
	s_waitcnt vmcnt(4)
	v_mov_b32_e32 v28, v208
	v_mov_b32_e32 v29, v209
	v_mov_b32_e32 v30, v210
	v_mov_b32_e32 v31, v211
	s_nop 0
	s_nop 1
	v_mov_b32_e32 v32, v212
	v_mov_b32_e32 v33, v213
	v_mov_b32_e32 v34, v214
	v_mov_b32_e32 v35, v215
	s_nop 0
	v_pk_fma_f32 v[22:23], v[22:23], v[70:71], v[30:31]
	v_pk_fma_f32 v[26:27], v[26:27], v[74:75], v[34:35]
	v_pk_fma_f32 v[24:25], v[24:25], v[72:73], v[32:33]
	v_pk_fma_f32 v[28:29], v[20:21], v[68:69], v[28:29]
	v_cvt_pk_f16_f32 v23, v22, v23
	v_cvt_pk_f16_f32 v21, v26, v27
	v_cvt_pk_f16_f32 v22, v28, v29
	v_cvt_pk_f16_f32 v20, v24, v25
	v_lshl_add_u64 v[28:29], v[170:171], 0, s[12:13]
	global_store_dwordx4 v[36:37], v[20:23], off offset:256
	v_lshl_add_u64 v[30:31], v[28:29], 2, s[80:81]
	s_nop 1
	s_waitcnt vmcnt(2)
	v_mov_b32_e32 v20, v216
	v_mov_b32_e32 v21, v217
	v_mov_b32_e32 v22, v218
	v_mov_b32_e32 v23, v219
	s_nop 1
	v_mov_b32_e32 v24, v220
	v_mov_b32_e32 v25, v221
	v_mov_b32_e32 v26, v222
	v_mov_b32_e32 v27, v223
	s_mov_b64 s[12:13], s[8:9]
	s_nop 0
	v_pk_fma_f32 v[14:15], v[14:15], v[86:87], v[22:23]
	v_pk_fma_f32 v[18:19], v[18:19], v[90:91], v[26:27]
	v_pk_fma_f32 v[16:17], v[16:17], v[88:89], v[24:25]
	v_pk_fma_f32 v[20:21], v[12:13], v[84:85], v[20:21]
	v_cvt_pk_f16_f32 v15, v14, v15
	v_cvt_pk_f16_f32 v13, v18, v19
	v_cvt_pk_f16_f32 v14, v20, v21
	v_cvt_pk_f16_f32 v12, v16, v17
	v_lshl_add_u64 v[20:21], v[28:29], 1, s[16:17]
	global_store_dwordx4 v[20:21], v[12:15], off
	s_nop 1
	s_waitcnt vmcnt(0)
	v_mov_b32_e32 v12, v224
	v_mov_b32_e32 v13, v225
	v_mov_b32_e32 v14, v226
	v_mov_b32_e32 v15, v227
	s_nop 0
	s_nop 1
	v_mov_b32_e32 v16, v228
	v_mov_b32_e32 v17, v229
	v_mov_b32_e32 v18, v230
	v_mov_b32_e32 v19, v231
	s_nop 0
	v_pk_fma_f32 v[6:7], v[6:7], v[70:71], v[14:15]
	v_pk_fma_f32 v[10:11], v[10:11], v[74:75], v[18:19]
	v_pk_fma_f32 v[8:9], v[8:9], v[72:73], v[16:17]
	v_pk_fma_f32 v[12:13], v[4:5], v[68:69], v[12:13]
	v_cvt_pk_f16_f32 v7, v6, v7
	v_cvt_pk_f16_f32 v5, v10, v11
	v_cvt_pk_f16_f32 v6, v12, v13
	v_cvt_pk_f16_f32 v4, v8, v9
	global_store_dwordx4 v[20:21], v[4:7], off offset:256
	s_cbranch_vccz .LBB0_671
	s_waitcnt vmcnt(0)
	v_readlane_b32 s42, v251, 7
	v_readlane_b32 s46, v251, 9
	v_readlane_b32 s48, v251, 13
	s_cmpk_gt_u32 s25, 0xff
	v_readlane_b32 s43, v251, 8
	v_readlane_b32 s47, v251, 10
	v_readlane_b32 s49, v251, 14
	s_cbranch_scc1 .LBB0_682
	s_barrier
